# SP4 K-loop for in_proj layers 0-2 (64 MFMA per barrier interval, asymmetric DMA staging) stacked on the epilogue trims
# baseline (speedup 1.0000x reference)
.LBB0_305:
.LBB0_306:
	v_readlane_b32 s6, v253, 31
	v_readlane_b32 s7, v253, 32
	s_add_u32 s10, s26, s6
	s_addc_u32 s11, s27, s7
	s_ashr_i32 s13, s0, 8
	s_add_i32 s97, s96, 0x2000
	s_mov_b32 m0, s96
	v_lshl_add_u32 v184, v0, 11, v1
	s_add_u32 s6, s10, 0x40000
	v_lshl_add_u32 v186, v2, 11, v3
	global_load_lds_dwordx4 v184, s[10:11]
	s_mov_b32 m0, s97
	s_addc_u32 s7, s11, 0
	s_add_i32 s40, s96, 0x4000
	global_load_lds_dwordx4 v186, s[10:11]
	s_mov_b32 m0, s40
	s_add_i32 s41, s96, 0x6000
	global_load_lds_dwordx4 v184, s[6:7]
	s_mov_b32 m0, s41
	s_waitcnt lgkmcnt(0)
	v_writelane_b32 v254, s52, 38
	global_load_lds_dwordx4 v186, s[6:7]
	s_nop 0
	v_writelane_b32 v254, s53, 39
	v_writelane_b32 v254, s48, 40
	v_mov_b32_e32 v183, v33
	v_mov_b32_e32 v35, v33
	v_writelane_b32 v254, s49, 41
	v_writelane_b32 v254, s43, 42
	v_writelane_b32 v254, s88, 43
	v_mov_b32_e32 v185, v33
	v_mov_b32_e32 v187, v33
	s_cmp_eq_u32 s13, 1
	v_writelane_b32 v254, s86, 45
	s_cselect_b64 s[48:49], -1, 0
	s_cmp_lg_u32 s13, 1
	s_waitcnt vmcnt(0)
	s_cbranch_scc1 .LBB0_308
	s_barrier
.LBB0_308:
	s_and_b32 s34, s12, 3
	s_lshl_b32 s100, s34, 10
	s_lshl_b32 s101, s13, 14
	s_add_i32 s100, s100, s101
	s_mul_i32 s101, s13, 0x30000
	v_add_u32_e32 v210, s101, v182
	v_add_u32_e32 v211, 0x10000, v210
	v_add_u32_e32 v212, s101, v34
	v_add_u32_e32 v213, 0x10000, v212
	v_add_u32_e32 v214, s101, v184
	v_add_u32_e32 v215, 0x10000, v214
	v_add_u32_e32 v218, s101, v186
	v_add_u32_e32 v219, 0x10000, v218
	s_mov_b32 s101, s13
	s_lshl_b32 s42, s13, 6
	s_lshl_b32 s12, s13, 13
	s_lshl_b32 s35, s34, 12
	s_barrier
	s_add_i32 s43, s96, 0x8000
	s_add_i32 s83, s96, 0xa000
	s_cmpk_lt_u32 s0, 0x100
	v_bfe_u32 v1, v8, 4, 2
	v_and_b32_e32 v204, 15, v8
	v_lshlrev_b32_e32 v0, 4, v1
	v_lshlrev_b32_e32 v3, 2, v8
	s_cselect_b64 s[52:53], -1, 0
	s_bitcmp0_b32 s0, 6
	v_lshl_or_b32 v2, v204, 6, v0
	v_and_b32_e32 v3, 32, v3
	s_cselect_b64 s[6:7], -1, 0
	s_lshl_b32 s0, s13, 2
	v_bitop3_b32 v4, v2, s12, v3 bitop3:0xde
	s_or_b32 s12, s0, s34
	s_ashr_i32 s13, s12, 31
	s_lshl_b64 s[12:13], s[12:13], 13
	v_bitop3_b32 v205, v2, s35, v3 bitop3:0xde
	v_lshlrev_b32_e32 v2, 4, v204
	s_add_u32 s12, s54, s12
	v_lshl_or_b32 v32, v1, 8, v2
	s_addc_u32 s13, s87, s13
	v_lshl_add_u64 v[190:191], s[12:13], 0, v[32:33]
	v_readlane_b32 s12, v253, 33
	v_writelane_b32 v254, s54, 46
	v_readlane_b32 s13, v253, 34
	v_lshl_or_b32 v2, s34, 6, v0
	v_mov_b32_e32 v3, v33
	v_writelane_b32 v254, s87, 47
	v_mov_b32_e32 v1, v33
	s_mov_b32 s87, s12
	v_readlane_b32 s12, v253, 37
	s_mov_b32 s82, 0
	v_or_b32_e32 v206, 16, v204
	v_or_b32_e32 v207, 32, v204
	v_or_b32_e32 v208, 48, v204
	v_lshl_add_u64 v[188:189], s[24:25], 0, v[2:3]
	v_lshl_add_u64 v[192:193], s[30:31], 0, v[0:1]
	v_lshl_add_u64 v[194:195], s[36:37], 0, v[0:1]
	v_add_u32_e32 v209, 0, v4
	v_add_u32_e32 v220, 0x10000, v205
	s_mov_b32 s88, s12
	v_readlane_b32 s13, v253, 38
	s_branch .LBB0_311

.LBB0_314:
.LBB0_315:
	s_or_b32 s92, s89, 1
	s_lshl_b64 s[76:77], s[92:93], 7
	s_add_u32 s78, s8, s76
	s_addc_u32 s79, s9, s77
	s_add_u32 s76, s10, s76
	s_addc_u32 s77, s11, s77
	s_add_i32 s92, s89, 2
	s_lshl_b64 s[80:81], s[92:93], 7
	s_add_u32 s0, s8, s80
	s_addc_u32 s54, s9, s81
	s_add_u32 s80, s10, s80
	s_addc_u32 s81, s11, s81
	s_and_b64 s[34:35], s[34:35], exec
	s_cselect_b32 s81, s81, s57
	s_cselect_b32 s80, s80, s66
	s_cselect_b32 s35, s54, s63
	s_cselect_b32 s34, s0, s90
	ds_read_b128 v[0:3], v220 offset:0
	ds_read_b128 v[4:7], v220 offset:1024
	ds_read_b128 v[8:11], v220 offset:2048
	ds_read_b128 v[12:15], v220 offset:3072
	ds_read_b128 v[16:19], v220 offset:16384
	ds_read_b128 v[20:23], v220 offset:17408
	ds_read_b128 v[24:27], v220 offset:18432
	ds_read_b128 v[28:31], v220 offset:19456
	s_add_i32 m0, s100, 0x8000
	ds_read_b128 v[166:169], v209 offset:0
	global_load_lds_dwordx4 v214, s[76:77]
	s_add_i32 m0, s100, 0x9000
	ds_read_b128 v[170:173], v209 offset:1024
	global_load_lds_dwordx4 v215, s[76:77]
	s_add_i32 m0, s100, 0xa000
	ds_read_b128 v[174:177], v209 offset:2048
	global_load_lds_dwordx4 v218, s[76:77]
	s_add_i32 m0, s100, 0xb000
	ds_read_b128 v[178:181], v209 offset:3072
	global_load_lds_dwordx4 v219, s[76:77]
	ds_read_b128 v[196:199], v209 offset:4096
	ds_read_b128 v[228:231], v209 offset:5120
	ds_read_b128 v[232:235], v209 offset:6144
	ds_read_b128 v[244:247], v209 offset:7168
	s_cmp_lg_u32 s101, 0
	s_cbranch_scc1 .Lsp4_a_skipB0
	s_add_u32 s76, s78, 0x40000
	s_addc_u32 s77, s79, 0
	s_add_i32 m0, s100, 0x18000
	s_nop 0
	global_load_lds_dwordx4 v210, s[78:79]
	s_add_i32 m0, s100, 0x19000
	s_nop 0
	global_load_lds_dwordx4 v211, s[78:79]
	s_add_i32 m0, s100, 0x1a000
	s_nop 0
	global_load_lds_dwordx4 v212, s[78:79]
	s_add_i32 m0, s100, 0x1b000
	s_nop 0
	global_load_lds_dwordx4 v213, s[78:79]
	s_add_i32 m0, s100, 0x1c000
	s_nop 0
	global_load_lds_dwordx4 v210, s[76:77]
	s_add_i32 m0, s100, 0x1d000
	s_nop 0
	global_load_lds_dwordx4 v211, s[76:77]
	s_add_i32 m0, s100, 0x1e000
	s_nop 0
	global_load_lds_dwordx4 v212, s[76:77]
	s_add_i32 m0, s100, 0x1f000
	s_nop 0
	global_load_lds_dwordx4 v213, s[76:77]
.Lsp4_a_skipB0:
	s_waitcnt lgkmcnt(0)
	s_barrier
	s_setprio 1
	v_mfma_f32_16x16x32_bf16 v[162:165], v[0:3], v[166:169], v[162:165]
	v_mfma_f32_16x16x32_bf16 v[158:161], v[8:11], v[166:169], v[158:161]
	v_mfma_f32_16x16x32_bf16 v[154:157], v[16:19], v[166:169], v[154:157]
	v_mfma_f32_16x16x32_bf16 v[150:153], v[24:27], v[166:169], v[150:153]
	v_mfma_f32_16x16x32_bf16 v[162:165], v[4:7], v[170:173], v[162:165]
	v_mfma_f32_16x16x32_bf16 v[158:161], v[12:15], v[170:173], v[158:161]
	v_mfma_f32_16x16x32_bf16 v[154:157], v[20:23], v[170:173], v[154:157]
	v_mfma_f32_16x16x32_bf16 v[150:153], v[28:31], v[170:173], v[150:153]
	ds_read_b128 v[166:169], v209 offset:16384
	ds_read_b128 v[170:173], v209 offset:17408
	v_mfma_f32_16x16x32_bf16 v[146:149], v[0:3], v[174:177], v[146:149]
	v_mfma_f32_16x16x32_bf16 v[142:145], v[8:11], v[174:177], v[142:145]
	v_mfma_f32_16x16x32_bf16 v[138:141], v[16:19], v[174:177], v[138:141]
	v_mfma_f32_16x16x32_bf16 v[134:137], v[24:27], v[174:177], v[134:137]
	v_mfma_f32_16x16x32_bf16 v[146:149], v[4:7], v[178:181], v[146:149]
	v_mfma_f32_16x16x32_bf16 v[142:145], v[12:15], v[178:181], v[142:145]
	v_mfma_f32_16x16x32_bf16 v[138:141], v[20:23], v[178:181], v[138:141]
	v_mfma_f32_16x16x32_bf16 v[134:137], v[28:31], v[178:181], v[134:137]
	ds_read_b128 v[174:177], v209 offset:18432
	ds_read_b128 v[178:181], v209 offset:19456
	v_mfma_f32_16x16x32_bf16 v[130:133], v[0:3], v[196:199], v[130:133]
	v_mfma_f32_16x16x32_bf16 v[126:129], v[8:11], v[196:199], v[126:129]
	v_mfma_f32_16x16x32_bf16 v[122:125], v[16:19], v[196:199], v[122:125]
	v_mfma_f32_16x16x32_bf16 v[118:121], v[24:27], v[196:199], v[118:121]
	v_mfma_f32_16x16x32_bf16 v[130:133], v[4:7], v[228:231], v[130:133]
	v_mfma_f32_16x16x32_bf16 v[126:129], v[12:15], v[228:231], v[126:129]
	v_mfma_f32_16x16x32_bf16 v[122:125], v[20:23], v[228:231], v[122:125]
	v_mfma_f32_16x16x32_bf16 v[118:121], v[28:31], v[228:231], v[118:121]
	ds_read_b128 v[196:199], v209 offset:20480
	ds_read_b128 v[228:231], v209 offset:21504
	v_mfma_f32_16x16x32_bf16 v[114:117], v[0:3], v[232:235], v[114:117]
	v_mfma_f32_16x16x32_bf16 v[110:113], v[8:11], v[232:235], v[110:113]
	v_mfma_f32_16x16x32_bf16 v[106:109], v[16:19], v[232:235], v[106:109]
	v_mfma_f32_16x16x32_bf16 v[102:105], v[24:27], v[232:235], v[102:105]
	v_mfma_f32_16x16x32_bf16 v[114:117], v[4:7], v[244:247], v[114:117]
	v_mfma_f32_16x16x32_bf16 v[110:113], v[12:15], v[244:247], v[110:113]
	v_mfma_f32_16x16x32_bf16 v[106:109], v[20:23], v[244:247], v[106:109]
	v_mfma_f32_16x16x32_bf16 v[102:105], v[28:31], v[244:247], v[102:105]
	ds_read_b128 v[232:235], v209 offset:22528
	ds_read_b128 v[244:247], v209 offset:23552
	s_waitcnt lgkmcnt(6)
	v_mfma_f32_16x16x32_bf16 v[98:101], v[0:3], v[166:169], v[98:101]
	v_mfma_f32_16x16x32_bf16 v[94:97], v[8:11], v[166:169], v[94:97]
	v_mfma_f32_16x16x32_bf16 v[90:93], v[16:19], v[166:169], v[90:93]
	v_mfma_f32_16x16x32_bf16 v[86:89], v[24:27], v[166:169], v[86:89]
	v_mfma_f32_16x16x32_bf16 v[98:101], v[4:7], v[170:173], v[98:101]
	v_mfma_f32_16x16x32_bf16 v[94:97], v[12:15], v[170:173], v[94:97]
	v_mfma_f32_16x16x32_bf16 v[90:93], v[20:23], v[170:173], v[90:93]
	v_mfma_f32_16x16x32_bf16 v[86:89], v[28:31], v[170:173], v[86:89]
	s_waitcnt lgkmcnt(4)
	v_mfma_f32_16x16x32_bf16 v[82:85], v[0:3], v[174:177], v[82:85]
	v_mfma_f32_16x16x32_bf16 v[78:81], v[8:11], v[174:177], v[78:81]
	v_mfma_f32_16x16x32_bf16 v[74:77], v[16:19], v[174:177], v[74:77]
	v_mfma_f32_16x16x32_bf16 v[70:73], v[24:27], v[174:177], v[70:73]
	v_mfma_f32_16x16x32_bf16 v[82:85], v[4:7], v[178:181], v[82:85]
	v_mfma_f32_16x16x32_bf16 v[78:81], v[12:15], v[178:181], v[78:81]
	v_mfma_f32_16x16x32_bf16 v[74:77], v[20:23], v[178:181], v[74:77]
	v_mfma_f32_16x16x32_bf16 v[70:73], v[28:31], v[178:181], v[70:73]
	s_waitcnt lgkmcnt(2)
	v_mfma_f32_16x16x32_bf16 v[66:69], v[0:3], v[196:199], v[66:69]
	v_mfma_f32_16x16x32_bf16 v[62:65], v[8:11], v[196:199], v[62:65]
	v_mfma_f32_16x16x32_bf16 v[58:61], v[16:19], v[196:199], v[58:61]
	v_mfma_f32_16x16x32_bf16 v[54:57], v[24:27], v[196:199], v[54:57]
	v_mfma_f32_16x16x32_bf16 v[66:69], v[4:7], v[228:231], v[66:69]
	v_mfma_f32_16x16x32_bf16 v[62:65], v[12:15], v[228:231], v[62:65]
	v_mfma_f32_16x16x32_bf16 v[58:61], v[20:23], v[228:231], v[58:61]
	v_mfma_f32_16x16x32_bf16 v[54:57], v[28:31], v[228:231], v[54:57]
	s_waitcnt lgkmcnt(0)
	v_mfma_f32_16x16x32_bf16 v[50:53], v[0:3], v[232:235], v[50:53]
	v_mfma_f32_16x16x32_bf16 v[46:49], v[8:11], v[232:235], v[46:49]
	v_mfma_f32_16x16x32_bf16 v[42:45], v[16:19], v[232:235], v[42:45]
	v_mfma_f32_16x16x32_bf16 v[38:41], v[24:27], v[232:235], v[38:41]
	v_mfma_f32_16x16x32_bf16 v[50:53], v[4:7], v[244:247], v[50:53]
	v_mfma_f32_16x16x32_bf16 v[46:49], v[12:15], v[244:247], v[46:49]
	v_mfma_f32_16x16x32_bf16 v[42:45], v[20:23], v[244:247], v[42:45]
	v_mfma_f32_16x16x32_bf16 v[38:41], v[28:31], v[244:247], v[38:41]
	s_setprio 0
	s_waitcnt vmcnt(0)
	s_barrier
	ds_read_b128 v[0:3], v220 offset:32768
	ds_read_b128 v[4:7], v220 offset:33792
	ds_read_b128 v[8:11], v220 offset:34816
	ds_read_b128 v[12:15], v220 offset:35840
	ds_read_b128 v[16:19], v220 offset:49152
	ds_read_b128 v[20:23], v220 offset:50176
	ds_read_b128 v[24:27], v220 offset:51200
	ds_read_b128 v[28:31], v220 offset:52224
	s_add_i32 m0, s100, 0x0
	ds_read_b128 v[166:169], v209 offset:32768
	global_load_lds_dwordx4 v214, s[80:81]
	s_add_i32 m0, s100, 0x1000
	ds_read_b128 v[170:173], v209 offset:33792
	global_load_lds_dwordx4 v215, s[80:81]
	s_add_i32 m0, s100, 0x2000
	ds_read_b128 v[174:177], v209 offset:34816
	global_load_lds_dwordx4 v218, s[80:81]
	s_add_i32 m0, s100, 0x3000
	ds_read_b128 v[178:181], v209 offset:35840
	global_load_lds_dwordx4 v219, s[80:81]
	ds_read_b128 v[196:199], v209 offset:36864
	ds_read_b128 v[228:231], v209 offset:37888
	ds_read_b128 v[232:235], v209 offset:38912
	ds_read_b128 v[244:247], v209 offset:39936
	s_cmp_lg_u32 s101, 0
	s_cbranch_scc1 .Lsp4_a_skipB1
	s_add_u32 s80, s34, 0x40000
	s_addc_u32 s81, s35, 0
	s_add_i32 m0, s100, 0x10000
	s_nop 0
	global_load_lds_dwordx4 v210, s[34:35]
	s_add_i32 m0, s100, 0x11000
	s_nop 0
	global_load_lds_dwordx4 v211, s[34:35]
	s_add_i32 m0, s100, 0x12000
	s_nop 0
	global_load_lds_dwordx4 v212, s[34:35]
	s_add_i32 m0, s100, 0x13000
	s_nop 0
	global_load_lds_dwordx4 v213, s[34:35]
	s_add_i32 m0, s100, 0x14000
	s_nop 0
	global_load_lds_dwordx4 v210, s[80:81]
	s_add_i32 m0, s100, 0x15000
	s_nop 0
	global_load_lds_dwordx4 v211, s[80:81]
	s_add_i32 m0, s100, 0x16000
	s_nop 0
	global_load_lds_dwordx4 v212, s[80:81]
	s_add_i32 m0, s100, 0x17000
	s_nop 0
	global_load_lds_dwordx4 v213, s[80:81]
.Lsp4_a_skipB1:
	s_waitcnt lgkmcnt(0)
	s_barrier
	s_setprio 1
	v_mfma_f32_16x16x32_bf16 v[162:165], v[0:3], v[166:169], v[162:165]
	v_mfma_f32_16x16x32_bf16 v[158:161], v[8:11], v[166:169], v[158:161]
	v_mfma_f32_16x16x32_bf16 v[154:157], v[16:19], v[166:169], v[154:157]
	v_mfma_f32_16x16x32_bf16 v[150:153], v[24:27], v[166:169], v[150:153]
	v_mfma_f32_16x16x32_bf16 v[162:165], v[4:7], v[170:173], v[162:165]
	v_mfma_f32_16x16x32_bf16 v[158:161], v[12:15], v[170:173], v[158:161]
	v_mfma_f32_16x16x32_bf16 v[154:157], v[20:23], v[170:173], v[154:157]
	v_mfma_f32_16x16x32_bf16 v[150:153], v[28:31], v[170:173], v[150:153]
	ds_read_b128 v[166:169], v209 offset:49152
	ds_read_b128 v[170:173], v209 offset:50176
	v_mfma_f32_16x16x32_bf16 v[146:149], v[0:3], v[174:177], v[146:149]
	v_mfma_f32_16x16x32_bf16 v[142:145], v[8:11], v[174:177], v[142:145]
	v_mfma_f32_16x16x32_bf16 v[138:141], v[16:19], v[174:177], v[138:141]
	v_mfma_f32_16x16x32_bf16 v[134:137], v[24:27], v[174:177], v[134:137]
	v_mfma_f32_16x16x32_bf16 v[146:149], v[4:7], v[178:181], v[146:149]
	v_mfma_f32_16x16x32_bf16 v[142:145], v[12:15], v[178:181], v[142:145]
	v_mfma_f32_16x16x32_bf16 v[138:141], v[20:23], v[178:181], v[138:141]
	v_mfma_f32_16x16x32_bf16 v[134:137], v[28:31], v[178:181], v[134:137]
	ds_read_b128 v[174:177], v209 offset:51200
	ds_read_b128 v[178:181], v209 offset:52224
	v_mfma_f32_16x16x32_bf16 v[130:133], v[0:3], v[196:199], v[130:133]
	v_mfma_f32_16x16x32_bf16 v[126:129], v[8:11], v[196:199], v[126:129]
	v_mfma_f32_16x16x32_bf16 v[122:125], v[16:19], v[196:199], v[122:125]
	v_mfma_f32_16x16x32_bf16 v[118:121], v[24:27], v[196:199], v[118:121]
	v_mfma_f32_16x16x32_bf16 v[130:133], v[4:7], v[228:231], v[130:133]
	v_mfma_f32_16x16x32_bf16 v[126:129], v[12:15], v[228:231], v[126:129]
	v_mfma_f32_16x16x32_bf16 v[122:125], v[20:23], v[228:231], v[122:125]
	v_mfma_f32_16x16x32_bf16 v[118:121], v[28:31], v[228:231], v[118:121]
	ds_read_b128 v[196:199], v209 offset:53248
	ds_read_b128 v[228:231], v209 offset:54272
	v_mfma_f32_16x16x32_bf16 v[114:117], v[0:3], v[232:235], v[114:117]
	v_mfma_f32_16x16x32_bf16 v[110:113], v[8:11], v[232:235], v[110:113]
	v_mfma_f32_16x16x32_bf16 v[106:109], v[16:19], v[232:235], v[106:109]
	v_mfma_f32_16x16x32_bf16 v[102:105], v[24:27], v[232:235], v[102:105]
	v_mfma_f32_16x16x32_bf16 v[114:117], v[4:7], v[244:247], v[114:117]
	v_mfma_f32_16x16x32_bf16 v[110:113], v[12:15], v[244:247], v[110:113]
	v_mfma_f32_16x16x32_bf16 v[106:109], v[20:23], v[244:247], v[106:109]
	v_mfma_f32_16x16x32_bf16 v[102:105], v[28:31], v[244:247], v[102:105]
	ds_read_b128 v[232:235], v209 offset:55296
	ds_read_b128 v[244:247], v209 offset:56320
	s_waitcnt lgkmcnt(6)
	v_mfma_f32_16x16x32_bf16 v[98:101], v[0:3], v[166:169], v[98:101]
	v_mfma_f32_16x16x32_bf16 v[94:97], v[8:11], v[166:169], v[94:97]
	v_mfma_f32_16x16x32_bf16 v[90:93], v[16:19], v[166:169], v[90:93]
	v_mfma_f32_16x16x32_bf16 v[86:89], v[24:27], v[166:169], v[86:89]
	v_mfma_f32_16x16x32_bf16 v[98:101], v[4:7], v[170:173], v[98:101]
	v_mfma_f32_16x16x32_bf16 v[94:97], v[12:15], v[170:173], v[94:97]
	v_mfma_f32_16x16x32_bf16 v[90:93], v[20:23], v[170:173], v[90:93]
	v_mfma_f32_16x16x32_bf16 v[86:89], v[28:31], v[170:173], v[86:89]
	s_waitcnt lgkmcnt(4)
	v_mfma_f32_16x16x32_bf16 v[82:85], v[0:3], v[174:177], v[82:85]
	v_mfma_f32_16x16x32_bf16 v[78:81], v[8:11], v[174:177], v[78:81]
	v_mfma_f32_16x16x32_bf16 v[74:77], v[16:19], v[174:177], v[74:77]
	v_mfma_f32_16x16x32_bf16 v[70:73], v[24:27], v[174:177], v[70:73]
	v_mfma_f32_16x16x32_bf16 v[82:85], v[4:7], v[178:181], v[82:85]
	v_mfma_f32_16x16x32_bf16 v[78:81], v[12:15], v[178:181], v[78:81]
	v_mfma_f32_16x16x32_bf16 v[74:77], v[20:23], v[178:181], v[74:77]
	v_mfma_f32_16x16x32_bf16 v[70:73], v[28:31], v[178:181], v[70:73]
	s_waitcnt lgkmcnt(2)
	v_mfma_f32_16x16x32_bf16 v[66:69], v[0:3], v[196:199], v[66:69]
	v_mfma_f32_16x16x32_bf16 v[62:65], v[8:11], v[196:199], v[62:65]
	v_mfma_f32_16x16x32_bf16 v[58:61], v[16:19], v[196:199], v[58:61]
	v_mfma_f32_16x16x32_bf16 v[54:57], v[24:27], v[196:199], v[54:57]
	v_mfma_f32_16x16x32_bf16 v[66:69], v[4:7], v[228:231], v[66:69]
	v_mfma_f32_16x16x32_bf16 v[62:65], v[12:15], v[228:231], v[62:65]
	v_mfma_f32_16x16x32_bf16 v[58:61], v[20:23], v[228:231], v[58:61]
	v_mfma_f32_16x16x32_bf16 v[54:57], v[28:31], v[228:231], v[54:57]
	s_waitcnt lgkmcnt(0)
	v_mfma_f32_16x16x32_bf16 v[50:53], v[0:3], v[232:235], v[50:53]
	v_mfma_f32_16x16x32_bf16 v[46:49], v[8:11], v[232:235], v[46:49]
	v_mfma_f32_16x16x32_bf16 v[42:45], v[16:19], v[232:235], v[42:45]
	v_mfma_f32_16x16x32_bf16 v[38:41], v[24:27], v[232:235], v[38:41]
	v_mfma_f32_16x16x32_bf16 v[50:53], v[4:7], v[244:247], v[50:53]
	v_mfma_f32_16x16x32_bf16 v[46:49], v[12:15], v[244:247], v[46:49]
	v_mfma_f32_16x16x32_bf16 v[42:45], v[20:23], v[244:247], v[42:45]
	v_mfma_f32_16x16x32_bf16 v[38:41], v[28:31], v[244:247], v[38:41]
	s_setprio 0
	s_waitcnt vmcnt(0)
	s_barrier
	s_add_i32 s89, s89, 2
	s_cmp_gt_u32 s89, 15
	s_cbranch_scc1 .LBB0_343

	.amdhsa_kernel _Z4mega1P
		.amdhsa_group_segment_fixed_size 0
		.amdhsa_private_segment_fixed_size 0
		.amdhsa_kernarg_size 432
		.amdhsa_user_sgpr_count 2
		.amdhsa_user_sgpr_dispatch_ptr 0
		.amdhsa_user_sgpr_queue_ptr 0
		.amdhsa_user_sgpr_kernarg_segment_ptr 1
		.amdhsa_user_sgpr_dispatch_id 0
		.amdhsa_user_sgpr_kernarg_preload_length 0
		.amdhsa_user_sgpr_kernarg_preload_offset 0
		.amdhsa_user_sgpr_private_segment_size 0
		.amdhsa_uses_dynamic_stack 0
		.amdhsa_enable_private_segment 0
		.amdhsa_system_sgpr_workgroup_id_x 1
		.amdhsa_system_sgpr_workgroup_id_y 0
		.amdhsa_system_sgpr_workgroup_id_z 0
		.amdhsa_system_sgpr_workgroup_info 0
		.amdhsa_system_vgpr_workitem_id 2
		.amdhsa_next_free_vgpr 256
		.amdhsa_next_free_sgpr 102
		.amdhsa_accum_offset 256
		.amdhsa_reserve_vcc 1
		.amdhsa_float_round_mode_32 0
		.amdhsa_float_round_mode_16_64 0
		.amdhsa_float_denorm_mode_32 3
		.amdhsa_float_denorm_mode_16_64 3
		.amdhsa_dx10_clamp 1
		.amdhsa_ieee_mode 1
		.amdhsa_fp16_overflow 0
		.amdhsa_tg_split 0
		.amdhsa_exception_fp_ieee_invalid_op 0
		.amdhsa_exception_fp_denorm_src 0
		.amdhsa_exception_fp_ieee_div_zero 0
		.amdhsa_exception_fp_ieee_overflow 0
		.amdhsa_exception_fp_ieee_underflow 0
		.amdhsa_exception_fp_ieee_inexact 0
		.amdhsa_exception_int_div_zero 0
	.end_amdhsa_kernel

amdhsa.kernels:
  - .agpr_count:     0
    .args:
      - .offset:         0
        .size:           176
        .value_kind:     by_value
      - .offset:         176
        .size:           4
        .value_kind:     hidden_block_count_x
      - .offset:         180
        .size:           4
        .value_kind:     hidden_block_count_y
      - .offset:         184
        .size:           4
        .value_kind:     hidden_block_count_z
      - .offset:         188
        .size:           2
        .value_kind:     hidden_group_size_x
      - .offset:         190
        .size:           2
        .value_kind:     hidden_group_size_y
      - .offset:         192
        .size:           2
        .value_kind:     hidden_group_size_z
      - .offset:         194
        .size:           2
        .value_kind:     hidden_remainder_x
      - .offset:         196
        .size:           2
        .value_kind:     hidden_remainder_y
      - .offset:         198
        .size:           2
        .value_kind:     hidden_remainder_z
      - .offset:         216
        .size:           8
        .value_kind:     hidden_global_offset_x
      - .offset:         224
        .size:           8
        .value_kind:     hidden_global_offset_y
      - .offset:         232
        .size:           8
        .value_kind:     hidden_global_offset_z
      - .offset:         240
        .size:           2
        .value_kind:     hidden_grid_dims
      - .offset:         264
        .size:           8
        .value_kind:     hidden_multigrid_sync_arg
      - .offset:         296
        .size:           4
        .value_kind:     hidden_dynamic_lds_size
    .group_segment_fixed_size: 0
    .kernarg_segment_align: 8
    .kernarg_segment_size: 432
    .language:       OpenCL C
    .language_version:
      - 2
      - 0
    .max_flat_workgroup_size: 512
    .name:           _Z4mega1P
    .private_segment_fixed_size: 0
    .sgpr_count:     108
    .sgpr_spill_count: 153
    .symbol:         _Z4mega1P.kd
    .uniform_work_group_size: 1
    .uses_dynamic_stack: false
    .vgpr_count:     256
    .vgpr_spill_count: 0
    .wavefront_size: 64
